# SGU head staging: four row-scale LDS reads issued together instead of four read-wait pairs
# baseline (speedup 1.0000x reference)
; #define LAS __attribute__((address_space(3)))
; __device__ __forceinline__ unsigned cvt_pk_bf16(float lo, float hi) { unsigned r; asm volatile("v_cvt_pk_bf16_f32 %0, %1, %2" : "=v"(r) : "v"(lo), "v"(hi)); return r; }
; __device__ __forceinline__ void sgu_phase(const Ctx& C, const bf16_t* Z1, const float* VSS, const float* gv, const bf16_t* WSB, const float* bs, bf16_t* Gout) {
;     ...
;                 const f32x4 ga = *(const f32x4*)(gv + 128 * h + 8 * ch), gb = *(const f32x4*)(gv + 128 * h + 8 * ch + 4);
; #pragma unroll
;                 for (int ps = 0; ps < 4; ++ps) { const int s = ps * 32 + srow; const u32x4 raw = vraw[ps]; const float r = rsv[s];
;                     u32x4 o; o.x = cvt_pk_bf16(bflo(raw.x) * r * ga[0], bfhi(raw.x) * r * ga[1]); o.y = cvt_pk_bf16(bflo(raw.y) * r * ga[2], bfhi(raw.y) * r * ga[3]);
;                     o.z = cvt_pk_bf16(bflo(raw.z) * r * gb[0], bfhi(raw.z) * r * gb[1]); o.w = cvt_pk_bf16(bflo(raw.w) * r * gb[2], bfhi(raw.w) * r * gb[3]);
;                     *(LAS u32x4*)(Vs + off_b(s, ch)) = o; }
.LBB0_220:
	v_mov_b64_e32 v[20:21], v[72:73]
	v_mov_b64_e32 v[22:23], v[74:75]
	v_mov_b64_e32 v[16:17], v[76:77]
	v_mov_b64_e32 v[18:19], v[78:79]
	ds_read_b32 v24, v183 offset:32768
	ds_read_b32 v26, v183 offset:32896
	ds_read_b32 v27, v183 offset:33024
	ds_read_b32 v28, v183 offset:33152
	v_lshlrev_b32_e32 v25, 16, v12
	v_and_b32_e32 v12, 0xffff0000, v12
	v_add_u32_e32 v115, v182, v184
	s_mov_b32 s22, 0x1f01000
	s_waitcnt lgkmcnt(0)
	v_mul_f32_e32 v25, v24, v25
	v_mul_f32_e32 v12, v24, v12
	v_mul_f32_e32 v25, v20, v25
	v_mul_f32_e32 v12, v21, v12
	v_cvt_pk_bf16_f32 v12, v25, v12
	v_lshlrev_b32_e32 v25, 16, v13
	v_and_b32_e32 v13, 0xffff0000, v13
	v_mul_f32_e32 v25, v24, v25
	v_mul_f32_e32 v13, v24, v13
	v_mul_f32_e32 v25, v22, v25
	v_mul_f32_e32 v13, v23, v13
	v_cvt_pk_bf16_f32 v13, v25, v13
	v_lshlrev_b32_e32 v25, 16, v14
	v_and_b32_e32 v14, 0xffff0000, v14
	v_mul_f32_e32 v25, v24, v25
	v_mul_f32_e32 v14, v24, v14
	v_mul_f32_e32 v25, v16, v25
	v_mul_f32_e32 v14, v17, v14
	v_cvt_pk_bf16_f32 v14, v25, v14
	v_lshlrev_b32_e32 v25, 16, v15
	v_and_b32_e32 v15, 0xffff0000, v15
	v_mul_f32_e32 v15, v24, v15
	v_mul_f32_e32 v25, v24, v25
	v_mul_f32_e32 v15, v19, v15
	v_mul_f32_e32 v25, v18, v25
	v_cvt_pk_bf16_f32 v15, v25, v15
	ds_write_b128 v115, v[12:15]
	v_lshlrev_b32_e32 v13, 16, v8
	v_and_b32_e32 v8, 0xffff0000, v8
	s_waitcnt lgkmcnt(0)
	v_mul_f32_e32 v13, v26, v13
	v_mul_f32_e32 v8, v26, v8
	v_mul_f32_e32 v13, v20, v13
	v_mul_f32_e32 v8, v21, v8
	v_cvt_pk_bf16_f32 v8, v13, v8
	v_lshlrev_b32_e32 v13, 16, v9
	v_and_b32_e32 v9, 0xffff0000, v9
	v_mul_f32_e32 v13, v26, v13
	v_mul_f32_e32 v9, v26, v9
	v_mul_f32_e32 v13, v22, v13
	v_mul_f32_e32 v9, v23, v9
	v_cvt_pk_bf16_f32 v9, v13, v9
	v_lshlrev_b32_e32 v13, 16, v10
	v_and_b32_e32 v10, 0xffff0000, v10
	v_mul_f32_e32 v13, v26, v13
	v_mul_f32_e32 v10, v26, v10
	v_mul_f32_e32 v13, v16, v13
	v_mul_f32_e32 v10, v17, v10
	v_cvt_pk_bf16_f32 v10, v13, v10
	v_lshlrev_b32_e32 v13, 16, v11
	v_and_b32_e32 v11, 0xffff0000, v11
	v_mul_f32_e32 v11, v26, v11
	v_mul_f32_e32 v13, v26, v13
	v_mul_f32_e32 v11, v19, v11
	v_mul_f32_e32 v13, v18, v13
	v_cvt_pk_bf16_f32 v11, v13, v11
	ds_write_b128 v230, v[8:11]
	v_lshlrev_b32_e32 v9, 16, v4
	v_and_b32_e32 v4, 0xffff0000, v4
	s_waitcnt lgkmcnt(0)
	v_mul_f32_e32 v9, v27, v9
	v_mul_f32_e32 v4, v27, v4
	v_mul_f32_e32 v9, v20, v9
	v_mul_f32_e32 v4, v21, v4
	v_cvt_pk_bf16_f32 v4, v9, v4
	v_lshlrev_b32_e32 v9, 16, v5
	v_and_b32_e32 v5, 0xffff0000, v5
	v_mul_f32_e32 v9, v27, v9
	v_mul_f32_e32 v5, v27, v5
	v_mul_f32_e32 v9, v22, v9
	v_mul_f32_e32 v5, v23, v5
	v_cvt_pk_bf16_f32 v5, v9, v5
	v_lshlrev_b32_e32 v9, 16, v6
	v_and_b32_e32 v6, 0xffff0000, v6
	v_mul_f32_e32 v9, v27, v9
	v_mul_f32_e32 v6, v27, v6
	v_mul_f32_e32 v9, v16, v9
	v_mul_f32_e32 v6, v17, v6
	v_cvt_pk_bf16_f32 v6, v9, v6
	v_lshlrev_b32_e32 v9, 16, v7
	v_and_b32_e32 v7, 0xffff0000, v7
	v_mul_f32_e32 v7, v27, v7
	v_mul_f32_e32 v9, v27, v9
	v_mul_f32_e32 v7, v19, v7
	v_mul_f32_e32 v9, v18, v9
	v_cvt_pk_bf16_f32 v7, v9, v7
	ds_write_b128 v231, v[4:7]
	v_lshlrev_b32_e32 v5, 16, v0
	v_and_b32_e32 v0, 0xffff0000, v0
	s_waitcnt lgkmcnt(0)
	v_mul_f32_e32 v5, v28, v5
	v_mul_f32_e32 v0, v28, v0
	v_mul_f32_e32 v5, v20, v5
	v_mul_f32_e32 v0, v21, v0
	v_cvt_pk_bf16_f32 v0, v5, v0
	v_lshlrev_b32_e32 v5, 16, v1
	v_and_b32_e32 v1, 0xffff0000, v1
	v_mul_f32_e32 v5, v28, v5
	v_mul_f32_e32 v1, v28, v1
	v_mul_f32_e32 v5, v22, v5
	v_mul_f32_e32 v1, v23, v1
	v_cvt_pk_bf16_f32 v1, v5, v1
	v_lshlrev_b32_e32 v5, 16, v2
	v_and_b32_e32 v2, 0xffff0000, v2
	v_mul_f32_e32 v5, v28, v5
	v_mul_f32_e32 v2, v28, v2
	v_mul_f32_e32 v5, v16, v5
	v_mul_f32_e32 v2, v17, v2
	v_cvt_pk_bf16_f32 v2, v5, v2
	v_lshlrev_b32_e32 v5, 16, v3
	v_and_b32_e32 v3, 0xffff0000, v3
	v_mul_f32_e32 v3, v28, v3
	v_mul_f32_e32 v5, v28, v5
	v_mul_f32_e32 v3, v19, v3
	v_mul_f32_e32 v5, v18, v5
	v_cvt_pk_bf16_f32 v3, v5, v3
	ds_write_b128 v232, v[0:3]
	v_lshl_add_u64 v[16:17], s[66:67], 0, v[158:159]
	v_add_co_u32_e32 v20, vcc, s22, v16
	s_nop 1
	v_addc_co_u32_e32 v21, vcc, 0, v17, vcc
	global_load_dwordx4 v[16:19], v[20:21], off offset:-4096
	global_load_dwordx4 v[76:79], v[20:21], off
	v_lshl_add_u64 v[20:21], s[66:67], 0, v[160:161]
	v_add_co_u32_e32 v20, vcc, s22, v20
	s_nop 1
	v_addc_co_u32_e32 v21, vcc, 0, v21, vcc
	global_load_dwordx4 v[68:71], v[20:21], off offset:-4096
	global_load_dwordx4 v[72:75], v[20:21], off
	v_lshl_add_u64 v[20:21], s[66:67], 0, v[162:163]
	v_add_co_u32_e32 v20, vcc, s22, v20
	s_nop 1
	v_addc_co_u32_e32 v21, vcc, 0, v21, vcc
	global_load_dwordx4 v[56:59], v[20:21], off offset:-4096
	global_load_dwordx4 v[60:63], v[20:21], off
	v_lshl_add_u64 v[20:21], s[66:67], 0, v[164:165]
	v_add_co_u32_e32 v20, vcc, s22, v20
	s_nop 1
	v_addc_co_u32_e32 v21, vcc, 0, v21, vcc
	global_load_dwordx4 v[48:51], v[20:21], off offset:-4096
	global_load_dwordx4 v[52:55], v[20:21], off
	v_lshl_add_u64 v[20:21], s[66:67], 0, v[154:155]
	global_load_dwordx2 v[180:181], v[20:21], off offset:-64
	global_load_dwordx2 v[178:179], v[20:21], off offset:-32
	global_load_dwordx2 v[176:177], v[20:21], off
	global_load_dwordx2 v[174:175], v[20:21], off offset:32
	v_lshl_add_u64 v[20:21], s[66:67], 0, v[156:157]
	global_load_dwordx2 v[172:173], v[20:21], off offset:-64
	global_load_dwordx2 v[170:171], v[20:21], off offset:-32
	global_load_dwordx2 v[168:169], v[20:21], off
	global_load_dwordx2 v[166:167], v[20:21], off offset:32
	v_lshl_add_u64 v[0:1], s[66:67], 0, v[142:143]
	global_load_dwordx4 v[12:15], v[0:1], off
	v_lshl_add_u64 v[0:1], s[66:67], 0, v[144:145]
	global_load_dwordx4 v[8:11], v[0:1], off
	v_lshl_add_u64 v[0:1], s[66:67], 0, v[146:147]
	global_load_dwordx4 v[4:7], v[0:1], off
	v_lshl_add_u64 v[0:1], s[66:67], 0, v[148:149]
	global_load_dwordx4 v[0:3], v[0:1], off
	v_cndmask_b32_e64 v20, 0, 1, s[54:55]
	v_cmp_ne_u32_e64 s[40:41], 1, v20
	s_andn2_b64 vcc, exec, s[54:55]
	s_waitcnt lgkmcnt(0)
	s_barrier
	s_cbranch_vccnz .LBB0_222
	ds_read_b64_tr_b16 v[28:29], v185
	ds_read_b64_tr_b16 v[30:31], v186
	ds_read_b64_tr_b16 v[24:25], v187
	ds_read_b64_tr_b16 v[26:27], v188
	ds_read_b64_tr_b16 v[20:21], v189
	ds_read_b64_tr_b16 v[22:23], v190
	ds_read_b64_tr_b16 v[234:235], v191
	ds_read_b64_tr_b16 v[236:237], v192
	s_waitcnt lgkmcnt(0)
	s_waitcnt vmcnt(19)
	v_mfma_f32_16x16x32_bf16 v[44:47], v[28:31], v[16:19], 0
	s_waitcnt vmcnt(18)
	v_mfma_f32_16x16x32_bf16 v[28:31], v[28:31], v[76:79], 0
	v_mfma_f32_16x16x32_bf16 v[40:43], v[24:27], v[16:19], 0
	v_mfma_f32_16x16x32_bf16 v[24:27], v[24:27], v[76:79], 0
	v_mfma_f32_16x16x32_bf16 v[36:39], v[20:23], v[16:19], 0
	v_mfma_f32_16x16x32_bf16 v[20:23], v[20:23], v[76:79], 0
	v_mfma_f32_16x16x32_bf16 v[32:35], v[234:237], v[16:19], 0
	v_mfma_f32_16x16x32_bf16 v[16:19], v[234:237], v[76:79], 0
	v_cndmask_b32_e64 v64, 0, 1, s[56:57]
	v_cmp_ne_u32_e64 s[42:43], 1, v64
	s_andn2_b64 vcc, exec, s[56:57]
	s_cbranch_vccz .LBB0_223
	s_branch .LBB0_224
